# loop-edge edit in steady attention loops: loop-exit compare hoisted above the barrier, redundant lgkmcnt(0) before barrier removed
# baseline (speedup 1.0000x reference)
; #define ATT_BAR() do { asm volatile("s_waitcnt lgkmcnt(0)" ::: "memory"); __builtin_amdgcn_s_barrier(); asm volatile("" ::: "memory"); } while (0)
; #define ATT_EVEN(j_, k2_, v1_) do { if (!F32) { if ((j_) + 2 < nt) ATT_DMAK((j_) + 2, k2_); if ((j_) + 1 < nt) ATT_DMAV((j_) + 1, v1_); } } while (0)
; template <bool F32>
; __device__ __forceinline__ void attn_unit(const AUnit& U, LAS unsigned char* lds, float lam, const float* subg) {
;     ...
;     } else {
; #pragma unroll 1
;         for (int it = 0; it <= nt; ++it) {
;             ATT_EVEN(it, r0, r2);
;             if (it >= 1 && it <= mnt) ATT_SM(it - 1);
;             ATT_MM((it >= 1 && it <= mnt), (it < mnt), r0, r1);
;             ATT_ODD(it, r2, r1);
;             ATT_BAR();
;             { const int t_ = r0; r0 = r1; r1 = r2; r2 = t_; }
;         }
.Lc1_st0:
	s_add_u32 s28, s22, 0x1fe0000
	s_addc_u32 s29, s23, 0
	s_mov_b32 m0, s8
	s_nop 0
	global_load_lds_dwordx4 v146, s[22:23]
	s_addk_i32 m0, 0x400
	s_nop 0
	global_load_lds_dwordx4 v148, s[22:23]
	s_add_i32 m0, s92, 0x8000
	s_nop 0
	global_load_lds_dwordx4 v150, s[28:29]
	s_addk_i32 m0, 0x400
	s_nop 0
	global_load_lds_dwordx4 v152, s[28:29]
	v_exp_f32_e32 v80, v80
	v_exp_f32_e32 v81, v81
	v_exp_f32_e32 v82, v82
	v_exp_f32_e32 v83, v83
	v_exp_f32_e32 v84, v84
	v_exp_f32_e32 v85, v85
	v_exp_f32_e32 v86, v86
	v_exp_f32_e32 v87, v87
	v_add_f32_e32 v2, v80, v84
	v_add_f32_e32 v3, v81, v85
	v_add_f32_e32 v4, v82, v86
	v_add_f32_e32 v5, v83, v87
	v_cvt_pk_bf16_f32 v128, v80, v81
	v_cvt_pk_bf16_f32 v129, v82, v83
	v_exp_f32_e32 v88, v88
	v_exp_f32_e32 v89, v89
	v_exp_f32_e32 v90, v90
	v_exp_f32_e32 v91, v91
	v_cvt_pk_bf16_f32 v130, v84, v85
	v_cvt_pk_bf16_f32 v131, v86, v87
	v_add_f32_e32 v2, v2, v88
	v_add_f32_e32 v3, v3, v89
	v_add_f32_e32 v4, v4, v90
	v_add_f32_e32 v5, v5, v91
	v_exp_f32_e32 v92, v92
	v_exp_f32_e32 v93, v93
	v_exp_f32_e32 v94, v94
	v_exp_f32_e32 v95, v95
	v_cvt_pk_bf16_f32 v132, v88, v89
	v_cvt_pk_bf16_f32 v133, v90, v91
	v_add_f32_e32 v2, v2, v92
	v_add_f32_e32 v3, v3, v93
	v_add_f32_e32 v4, v4, v94
	v_add_f32_e32 v5, v5, v95
	v_exp_f32_e32 v96, v96
	v_exp_f32_e32 v97, v97
	v_exp_f32_e32 v98, v98
	v_exp_f32_e32 v99, v99
	v_cvt_pk_bf16_f32 v134, v92, v93
	v_cvt_pk_bf16_f32 v135, v94, v95
	v_add_f32_e32 v2, v2, v96
	v_add_f32_e32 v3, v3, v97
	v_add_f32_e32 v4, v4, v98
	v_add_f32_e32 v5, v5, v99
	v_exp_f32_e32 v100, v100
	v_exp_f32_e32 v101, v101
	v_exp_f32_e32 v102, v102
	v_exp_f32_e32 v103, v103
	v_cvt_pk_bf16_f32 v136, v96, v97
	v_cvt_pk_bf16_f32 v137, v98, v99
	v_add_f32_e32 v2, v2, v100
	v_add_f32_e32 v3, v3, v101
	v_add_f32_e32 v4, v4, v102
	v_add_f32_e32 v5, v5, v103
	v_exp_f32_e32 v104, v104
	v_exp_f32_e32 v105, v105
	v_exp_f32_e32 v106, v106
	v_exp_f32_e32 v107, v107
	v_cvt_pk_bf16_f32 v138, v100, v101
	v_cvt_pk_bf16_f32 v139, v102, v103
	v_add_f32_e32 v2, v2, v104
	v_add_f32_e32 v3, v3, v105
	v_add_f32_e32 v4, v4, v106
	v_add_f32_e32 v5, v5, v107
	v_exp_f32_e32 v108, v108
	v_exp_f32_e32 v109, v109
	v_exp_f32_e32 v110, v110
	v_exp_f32_e32 v111, v111
	v_cvt_pk_bf16_f32 v140, v104, v105
	v_cvt_pk_bf16_f32 v141, v106, v107
	v_add_f32_e32 v2, v2, v108
	v_add_f32_e32 v3, v3, v109
	v_add_f32_e32 v4, v4, v110
	v_add_f32_e32 v5, v5, v111
	v_add_f32_e32 v2, v2, v3
	v_add_f32_e32 v4, v4, v5
	v_cvt_pk_bf16_f32 v142, v108, v109
	v_add_f32_e32 v2, v2, v4
	v_cvt_pk_bf16_f32 v143, v110, v111
	v_add_f32_e32 v165, v165, v2
	ds_read_b64_tr_b16 v[2:3], v0
	ds_read_b64_tr_b16 v[4:5], v14
	ds_read_b64_tr_b16 v[6:7], v15
	ds_read_b64_tr_b16 v[8:9], v171
	ds_read_b64_tr_b16 v[10:11], v180
	ds_read_b64_tr_b16 v[12:13], v181
	ds_read_b64_tr_b16 v[172:173], v253
	ds_read_b64_tr_b16 v[174:175], v254
	ds_read_b64_tr_b16 v[198:199], v0 offset:4096
	ds_read_b64_tr_b16 v[200:201], v14 offset:4096
	ds_read_b64_tr_b16 v[202:203], v15 offset:4096
	ds_read_b64_tr_b16 v[204:205], v171 offset:4096
	ds_read_b64_tr_b16 v[206:207], v180 offset:4096
	ds_read_b64_tr_b16 v[208:209], v181 offset:4096
	s_setprio 2
	s_waitcnt lgkmcnt(12)
	v_mfma_f32_32x32x16_bf16 v[64:79], v[2:5], v[128:131], v[64:79]
	ds_read_b64_tr_b16 v[176:177], v253 offset:4096
	ds_read_b64_tr_b16 v[178:179], v254 offset:4096
	s_waitcnt lgkmcnt(12)
	v_mfma_f32_32x32x16_bf16 v[48:63], v[6:9], v[128:131], v[48:63]
	ds_read_b64_tr_b16 v[2:3], v0 offset:8192
	ds_read_b64_tr_b16 v[4:5], v14 offset:8192
	s_waitcnt lgkmcnt(12)
	v_mfma_f32_32x32x16_bf16 v[32:47], v[10:13], v[128:131], v[32:47]
	ds_read_b64_tr_b16 v[6:7], v15 offset:8192
	ds_read_b64_tr_b16 v[8:9], v171 offset:8192
	s_waitcnt lgkmcnt(12)
	v_mfma_f32_32x32x16_bf16 v[16:31], v[172:175], v[128:131], v[16:31]
	ds_read_b64_tr_b16 v[10:11], v180 offset:8192
	ds_read_b64_tr_b16 v[12:13], v181 offset:8192
	s_waitcnt lgkmcnt(12)
	v_mfma_f32_32x32x16_bf16 v[64:79], v[198:201], v[132:135], v[64:79]
	ds_read_b64_tr_b16 v[172:173], v253 offset:8192
	ds_read_b64_tr_b16 v[174:175], v254 offset:8192
	s_waitcnt lgkmcnt(12)
	v_mfma_f32_32x32x16_bf16 v[48:63], v[202:205], v[132:135], v[48:63]
	ds_read_b64_tr_b16 v[198:199], v0 offset:12288
	ds_read_b64_tr_b16 v[200:201], v14 offset:12288
	s_waitcnt lgkmcnt(12)
	v_mfma_f32_32x32x16_bf16 v[32:47], v[206:209], v[132:135], v[32:47]
	ds_read_b64_tr_b16 v[202:203], v15 offset:12288
	ds_read_b64_tr_b16 v[204:205], v171 offset:12288
	s_waitcnt lgkmcnt(12)
	v_mfma_f32_32x32x16_bf16 v[16:31], v[176:179], v[132:135], v[16:31]
	ds_read_b64_tr_b16 v[206:207], v180 offset:12288
	ds_read_b64_tr_b16 v[208:209], v181 offset:12288
	s_waitcnt lgkmcnt(12)
	v_mfma_f32_32x32x16_bf16 v[64:79], v[2:5], v[136:139], v[64:79]
	ds_read_b64_tr_b16 v[176:177], v253 offset:12288
	ds_read_b64_tr_b16 v[178:179], v254 offset:12288
	s_waitcnt lgkmcnt(12)
	v_mfma_f32_32x32x16_bf16 v[48:63], v[6:9], v[136:139], v[48:63]
	ds_read_b128 v[2:5], v145 offset:16384
	s_waitcnt lgkmcnt(11)
	v_mfma_f32_32x32x16_bf16 v[32:47], v[10:13], v[136:139], v[32:47]
	ds_read_b128 v[6:9], v145 offset:24576
	s_waitcnt lgkmcnt(10)
	v_mfma_f32_32x32x16_bf16 v[16:31], v[172:175], v[136:139], v[16:31]
	ds_read_b128 v[10:13], v159 offset:16384
	s_waitcnt lgkmcnt(9)
	v_mfma_f32_32x32x16_bf16 v[64:79], v[198:201], v[140:143], v[64:79]
	ds_read_b128 v[172:175], v159 offset:24576
	s_waitcnt lgkmcnt(8)
	v_mfma_f32_32x32x16_bf16 v[48:63], v[202:205], v[140:143], v[48:63]
	ds_read_b128 v[198:201], v160 offset:16384
	s_waitcnt lgkmcnt(7)
	v_mfma_f32_32x32x16_bf16 v[32:47], v[206:209], v[140:143], v[32:47]
	ds_read_b128 v[202:205], v160 offset:24576
	s_waitcnt lgkmcnt(6)
	v_mfma_f32_32x32x16_bf16 v[16:31], v[176:179], v[140:143], v[16:31]
	ds_read_b128 v[206:209], v161 offset:16384
	ds_read_b128 v[176:179], v161 offset:24576
	s_waitcnt lgkmcnt(7)
	v_mfma_f32_32x32x16_bf16 v[80:95], v[2:5], v[112:115], 0
	s_waitcnt lgkmcnt(6)
	v_mfma_f32_32x32x16_bf16 v[96:111], v[6:9], v[112:115], 0
	s_waitcnt lgkmcnt(5)
	v_mfma_f32_32x32x16_bf16 v[80:95], v[10:13], v[116:119], v[80:95]
	s_waitcnt lgkmcnt(4)
	v_mfma_f32_32x32x16_bf16 v[96:111], v[172:175], v[116:119], v[96:111]
	s_waitcnt lgkmcnt(3)
	v_mfma_f32_32x32x16_bf16 v[80:95], v[198:201], v[120:123], v[80:95]
	s_waitcnt lgkmcnt(2)
	v_mfma_f32_32x32x16_bf16 v[96:111], v[202:205], v[120:123], v[96:111]
	s_waitcnt lgkmcnt(1)
	v_mfma_f32_32x32x16_bf16 v[80:95], v[206:209], v[124:127], v[80:95]
	s_waitcnt lgkmcnt(0)
	v_mfma_f32_32x32x16_bf16 v[96:111], v[176:179], v[124:127], v[96:111]
	s_setprio 1
	s_add_u32 s22, s22, 0x20000
	s_addc_u32 s23, s23, 0
	s_add_i32 s95, s95, 1
	s_cmp_lt_i32 s95, s30
	s_waitcnt vmcnt(4)
	s_barrier
	s_cbranch_scc1 .Lc1_st1
	s_mov_b32 s24, 0x4000
	s_mov_b32 s93, 0x8000
	s_mov_b32 s94, 0
	s_branch .LBB0_704
; #define ATT_BAR() do { asm volatile("s_waitcnt lgkmcnt(0)" ::: "memory"); __builtin_amdgcn_s_barrier(); asm volatile("" ::: "memory"); } while (0)
; #define ATT_EVEN(j_, k2_, v1_) do { if (!F32) { if ((j_) + 2 < nt) ATT_DMAK((j_) + 2, k2_); if ((j_) + 1 < nt) ATT_DMAV((j_) + 1, v1_); } } while (0)
; template <bool F32>
; __device__ __forceinline__ void attn_unit(const AUnit& U, LAS unsigned char* lds, float lam, const float* subg) {
;     ...
;     } else {
; #pragma unroll 1
;         for (int it = 0; it <= nt; ++it) {
;             ATT_EVEN(it, r0, r2);
;             if (it >= 1 && it <= mnt) ATT_SM(it - 1);
;             ATT_MM((it >= 1 && it <= mnt), (it < mnt), r0, r1);
;             ATT_ODD(it, r2, r1);
;             ATT_BAR();
;             { const int t_ = r0; r0 = r1; r1 = r2; r2 = t_; }
;         }
.Lc1_st1:
	s_add_u32 s28, s22, 0x1fe0000
	s_addc_u32 s29, s23, 0
	s_add_i32 m0, s8, 0x4000
	s_nop 0
	global_load_lds_dwordx4 v146, s[22:23]
	s_addk_i32 m0, 0x400
	s_nop 0
	global_load_lds_dwordx4 v148, s[22:23]
	s_mov_b32 m0, s92
	s_nop 0
	global_load_lds_dwordx4 v150, s[28:29]
	s_addk_i32 m0, 0x400
	s_nop 0
	global_load_lds_dwordx4 v152, s[28:29]
	v_exp_f32_e32 v80, v80
	v_exp_f32_e32 v81, v81
	v_exp_f32_e32 v82, v82
	v_exp_f32_e32 v83, v83
	v_exp_f32_e32 v84, v84
	v_exp_f32_e32 v85, v85
	v_exp_f32_e32 v86, v86
	v_exp_f32_e32 v87, v87
	v_add_f32_e32 v2, v80, v84
	v_add_f32_e32 v3, v81, v85
	v_add_f32_e32 v4, v82, v86
	v_add_f32_e32 v5, v83, v87
	v_cvt_pk_bf16_f32 v128, v80, v81
	v_cvt_pk_bf16_f32 v129, v82, v83
	v_exp_f32_e32 v88, v88
	v_exp_f32_e32 v89, v89
	v_exp_f32_e32 v90, v90
	v_exp_f32_e32 v91, v91
	v_cvt_pk_bf16_f32 v130, v84, v85
	v_cvt_pk_bf16_f32 v131, v86, v87
	v_add_f32_e32 v2, v2, v88
	v_add_f32_e32 v3, v3, v89
	v_add_f32_e32 v4, v4, v90
	v_add_f32_e32 v5, v5, v91
	v_exp_f32_e32 v92, v92
	v_exp_f32_e32 v93, v93
	v_exp_f32_e32 v94, v94
	v_exp_f32_e32 v95, v95
	v_cvt_pk_bf16_f32 v132, v88, v89
	v_cvt_pk_bf16_f32 v133, v90, v91
	v_add_f32_e32 v2, v2, v92
	v_add_f32_e32 v3, v3, v93
	v_add_f32_e32 v4, v4, v94
	v_add_f32_e32 v5, v5, v95
	v_exp_f32_e32 v96, v96
	v_exp_f32_e32 v97, v97
	v_exp_f32_e32 v98, v98
	v_exp_f32_e32 v99, v99
	v_cvt_pk_bf16_f32 v134, v92, v93
	v_cvt_pk_bf16_f32 v135, v94, v95
	v_add_f32_e32 v2, v2, v96
	v_add_f32_e32 v3, v3, v97
	v_add_f32_e32 v4, v4, v98
	v_add_f32_e32 v5, v5, v99
	v_exp_f32_e32 v100, v100
	v_exp_f32_e32 v101, v101
	v_exp_f32_e32 v102, v102
	v_exp_f32_e32 v103, v103
	v_cvt_pk_bf16_f32 v136, v96, v97
	v_cvt_pk_bf16_f32 v137, v98, v99
	v_add_f32_e32 v2, v2, v100
	v_add_f32_e32 v3, v3, v101
	v_add_f32_e32 v4, v4, v102
	v_add_f32_e32 v5, v5, v103
	v_exp_f32_e32 v104, v104
	v_exp_f32_e32 v105, v105
	v_exp_f32_e32 v106, v106
	v_exp_f32_e32 v107, v107
	v_cvt_pk_bf16_f32 v138, v100, v101
	v_cvt_pk_bf16_f32 v139, v102, v103
	v_add_f32_e32 v2, v2, v104
	v_add_f32_e32 v3, v3, v105
	v_add_f32_e32 v4, v4, v106
	v_add_f32_e32 v5, v5, v107
	v_exp_f32_e32 v108, v108
	v_exp_f32_e32 v109, v109
	v_exp_f32_e32 v110, v110
	v_exp_f32_e32 v111, v111
	v_cvt_pk_bf16_f32 v140, v104, v105
	v_cvt_pk_bf16_f32 v141, v106, v107
	v_add_f32_e32 v2, v2, v108
	v_add_f32_e32 v3, v3, v109
	v_add_f32_e32 v4, v4, v110
	v_add_f32_e32 v5, v5, v111
	v_add_f32_e32 v2, v2, v3
	v_add_f32_e32 v4, v4, v5
	v_cvt_pk_bf16_f32 v142, v108, v109
	v_add_f32_e32 v2, v2, v4
	v_cvt_pk_bf16_f32 v143, v110, v111
	v_add_f32_e32 v165, v165, v2
	ds_read_b64_tr_b16 v[2:3], v0 offset:16384
	ds_read_b64_tr_b16 v[4:5], v14 offset:16384
	ds_read_b64_tr_b16 v[6:7], v15 offset:16384
	ds_read_b64_tr_b16 v[8:9], v171 offset:16384
	ds_read_b64_tr_b16 v[10:11], v180 offset:16384
	ds_read_b64_tr_b16 v[12:13], v181 offset:16384
	ds_read_b64_tr_b16 v[172:173], v253 offset:16384
	ds_read_b64_tr_b16 v[174:175], v254 offset:16384
	ds_read_b64_tr_b16 v[198:199], v0 offset:20480
	ds_read_b64_tr_b16 v[200:201], v14 offset:20480
	ds_read_b64_tr_b16 v[202:203], v15 offset:20480
	ds_read_b64_tr_b16 v[204:205], v171 offset:20480
	ds_read_b64_tr_b16 v[206:207], v180 offset:20480
	ds_read_b64_tr_b16 v[208:209], v181 offset:20480
	s_setprio 2
	s_waitcnt lgkmcnt(12)
	v_mfma_f32_32x32x16_bf16 v[64:79], v[2:5], v[128:131], v[64:79]
	ds_read_b64_tr_b16 v[176:177], v253 offset:20480
	ds_read_b64_tr_b16 v[178:179], v254 offset:20480
	s_waitcnt lgkmcnt(12)
	v_mfma_f32_32x32x16_bf16 v[48:63], v[6:9], v[128:131], v[48:63]
	ds_read_b64_tr_b16 v[2:3], v0 offset:24576
	ds_read_b64_tr_b16 v[4:5], v14 offset:24576
	s_waitcnt lgkmcnt(12)
	v_mfma_f32_32x32x16_bf16 v[32:47], v[10:13], v[128:131], v[32:47]
	ds_read_b64_tr_b16 v[6:7], v15 offset:24576
	ds_read_b64_tr_b16 v[8:9], v171 offset:24576
	s_waitcnt lgkmcnt(12)
	v_mfma_f32_32x32x16_bf16 v[16:31], v[172:175], v[128:131], v[16:31]
	ds_read_b64_tr_b16 v[10:11], v180 offset:24576
	ds_read_b64_tr_b16 v[12:13], v181 offset:24576
	s_waitcnt lgkmcnt(12)
	v_mfma_f32_32x32x16_bf16 v[64:79], v[198:201], v[132:135], v[64:79]
	ds_read_b64_tr_b16 v[172:173], v253 offset:24576
	ds_read_b64_tr_b16 v[174:175], v254 offset:24576
	s_waitcnt lgkmcnt(12)
	v_mfma_f32_32x32x16_bf16 v[48:63], v[202:205], v[132:135], v[48:63]
	ds_read_b64_tr_b16 v[198:199], v0 offset:28672
	ds_read_b64_tr_b16 v[200:201], v14 offset:28672
	s_waitcnt lgkmcnt(12)
	v_mfma_f32_32x32x16_bf16 v[32:47], v[206:209], v[132:135], v[32:47]
	ds_read_b64_tr_b16 v[202:203], v15 offset:28672
	ds_read_b64_tr_b16 v[204:205], v171 offset:28672
	s_waitcnt lgkmcnt(12)
	v_mfma_f32_32x32x16_bf16 v[16:31], v[176:179], v[132:135], v[16:31]
	ds_read_b64_tr_b16 v[206:207], v180 offset:28672
	ds_read_b64_tr_b16 v[208:209], v181 offset:28672
	s_waitcnt lgkmcnt(12)
	v_mfma_f32_32x32x16_bf16 v[64:79], v[2:5], v[136:139], v[64:79]
	ds_read_b64_tr_b16 v[176:177], v253 offset:28672
	ds_read_b64_tr_b16 v[178:179], v254 offset:28672
	s_waitcnt lgkmcnt(12)
	v_mfma_f32_32x32x16_bf16 v[48:63], v[6:9], v[136:139], v[48:63]
	ds_read_b128 v[2:5], v145 offset:32768
	s_waitcnt lgkmcnt(11)
	v_mfma_f32_32x32x16_bf16 v[32:47], v[10:13], v[136:139], v[32:47]
	ds_read_b128 v[6:9], v145 offset:40960
	s_waitcnt lgkmcnt(10)
	v_mfma_f32_32x32x16_bf16 v[16:31], v[172:175], v[136:139], v[16:31]
	ds_read_b128 v[10:13], v159 offset:32768
	s_waitcnt lgkmcnt(9)
	v_mfma_f32_32x32x16_bf16 v[64:79], v[198:201], v[140:143], v[64:79]
	ds_read_b128 v[172:175], v159 offset:40960
	s_waitcnt lgkmcnt(8)
	v_mfma_f32_32x32x16_bf16 v[48:63], v[202:205], v[140:143], v[48:63]
	ds_read_b128 v[198:201], v160 offset:32768
	s_waitcnt lgkmcnt(7)
	v_mfma_f32_32x32x16_bf16 v[32:47], v[206:209], v[140:143], v[32:47]
	ds_read_b128 v[202:205], v160 offset:40960
	s_waitcnt lgkmcnt(6)
	v_mfma_f32_32x32x16_bf16 v[16:31], v[176:179], v[140:143], v[16:31]
	ds_read_b128 v[206:209], v161 offset:32768
	ds_read_b128 v[176:179], v161 offset:40960
	s_waitcnt lgkmcnt(7)
	v_mfma_f32_32x32x16_bf16 v[80:95], v[2:5], v[112:115], 0
	s_waitcnt lgkmcnt(6)
	v_mfma_f32_32x32x16_bf16 v[96:111], v[6:9], v[112:115], 0
	s_waitcnt lgkmcnt(5)
	v_mfma_f32_32x32x16_bf16 v[80:95], v[10:13], v[116:119], v[80:95]
	s_waitcnt lgkmcnt(4)
	v_mfma_f32_32x32x16_bf16 v[96:111], v[172:175], v[116:119], v[96:111]
	s_waitcnt lgkmcnt(3)
	v_mfma_f32_32x32x16_bf16 v[80:95], v[198:201], v[120:123], v[80:95]
	s_waitcnt lgkmcnt(2)
	v_mfma_f32_32x32x16_bf16 v[96:111], v[202:205], v[120:123], v[96:111]
	s_waitcnt lgkmcnt(1)
	v_mfma_f32_32x32x16_bf16 v[80:95], v[206:209], v[124:127], v[80:95]
	s_waitcnt lgkmcnt(0)
	v_mfma_f32_32x32x16_bf16 v[96:111], v[176:179], v[124:127], v[96:111]
	s_setprio 1
	s_add_u32 s22, s22, 0x20000
	s_addc_u32 s23, s23, 0
	s_add_i32 s95, s95, 1
	s_cmp_lt_i32 s95, s30
	s_waitcnt vmcnt(4)
	s_barrier
	s_cbranch_scc1 .Lc1_st2
	s_mov_b32 s24, 0x8000
	s_mov_b32 s93, 0
	s_mov_b32 s94, 0x4000
	s_branch .LBB0_704
; #define ATT_BAR() do { asm volatile("s_waitcnt lgkmcnt(0)" ::: "memory"); __builtin_amdgcn_s_barrier(); asm volatile("" ::: "memory"); } while (0)
; #define ATT_EVEN(j_, k2_, v1_) do { if (!F32) { if ((j_) + 2 < nt) ATT_DMAK((j_) + 2, k2_); if ((j_) + 1 < nt) ATT_DMAV((j_) + 1, v1_); } } while (0)
; template <bool F32>
; __device__ __forceinline__ void attn_unit(const AUnit& U, LAS unsigned char* lds, float lam, const float* subg) {
;     ...
;     } else {
; #pragma unroll 1
;         for (int it = 0; it <= nt; ++it) {
;             ATT_EVEN(it, r0, r2);
;             if (it >= 1 && it <= mnt) ATT_SM(it - 1);
;             ATT_MM((it >= 1 && it <= mnt), (it < mnt), r0, r1);
;             ATT_ODD(it, r2, r1);
;             ATT_BAR();
;             { const int t_ = r0; r0 = r1; r1 = r2; r2 = t_; }
;         }
.Lc1_st2:
	s_add_u32 s28, s22, 0x1fe0000
	s_addc_u32 s29, s23, 0
	s_add_i32 m0, s8, 0x8000
	s_nop 0
	global_load_lds_dwordx4 v146, s[22:23]
	s_addk_i32 m0, 0x400
	s_nop 0
	global_load_lds_dwordx4 v148, s[22:23]
	s_add_i32 m0, s92, 0x4000
	s_nop 0
	global_load_lds_dwordx4 v150, s[28:29]
	s_addk_i32 m0, 0x400
	s_nop 0
	global_load_lds_dwordx4 v152, s[28:29]
	v_exp_f32_e32 v80, v80
	v_exp_f32_e32 v81, v81
	v_exp_f32_e32 v82, v82
	v_exp_f32_e32 v83, v83
	v_exp_f32_e32 v84, v84
	v_exp_f32_e32 v85, v85
	v_exp_f32_e32 v86, v86
	v_exp_f32_e32 v87, v87
	v_add_f32_e32 v2, v80, v84
	v_add_f32_e32 v3, v81, v85
	v_add_f32_e32 v4, v82, v86
	v_add_f32_e32 v5, v83, v87
	v_cvt_pk_bf16_f32 v128, v80, v81
	v_cvt_pk_bf16_f32 v129, v82, v83
	v_exp_f32_e32 v88, v88
	v_exp_f32_e32 v89, v89
	v_exp_f32_e32 v90, v90
	v_exp_f32_e32 v91, v91
	v_cvt_pk_bf16_f32 v130, v84, v85
	v_cvt_pk_bf16_f32 v131, v86, v87
	v_add_f32_e32 v2, v2, v88
	v_add_f32_e32 v3, v3, v89
	v_add_f32_e32 v4, v4, v90
	v_add_f32_e32 v5, v5, v91
	v_exp_f32_e32 v92, v92
	v_exp_f32_e32 v93, v93
	v_exp_f32_e32 v94, v94
	v_exp_f32_e32 v95, v95
	v_cvt_pk_bf16_f32 v132, v88, v89
	v_cvt_pk_bf16_f32 v133, v90, v91
	v_add_f32_e32 v2, v2, v92
	v_add_f32_e32 v3, v3, v93
	v_add_f32_e32 v4, v4, v94
	v_add_f32_e32 v5, v5, v95
	v_exp_f32_e32 v96, v96
	v_exp_f32_e32 v97, v97
	v_exp_f32_e32 v98, v98
	v_exp_f32_e32 v99, v99
	v_cvt_pk_bf16_f32 v134, v92, v93
	v_cvt_pk_bf16_f32 v135, v94, v95
	v_add_f32_e32 v2, v2, v96
	v_add_f32_e32 v3, v3, v97
	v_add_f32_e32 v4, v4, v98
	v_add_f32_e32 v5, v5, v99
	v_exp_f32_e32 v100, v100
	v_exp_f32_e32 v101, v101
	v_exp_f32_e32 v102, v102
	v_exp_f32_e32 v103, v103
	v_cvt_pk_bf16_f32 v136, v96, v97
	v_cvt_pk_bf16_f32 v137, v98, v99
	v_add_f32_e32 v2, v2, v100
	v_add_f32_e32 v3, v3, v101
	v_add_f32_e32 v4, v4, v102
	v_add_f32_e32 v5, v5, v103
	v_exp_f32_e32 v104, v104
	v_exp_f32_e32 v105, v105
	v_exp_f32_e32 v106, v106
	v_exp_f32_e32 v107, v107
	v_cvt_pk_bf16_f32 v138, v100, v101
	v_cvt_pk_bf16_f32 v139, v102, v103
	v_add_f32_e32 v2, v2, v104
	v_add_f32_e32 v3, v3, v105
	v_add_f32_e32 v4, v4, v106
	v_add_f32_e32 v5, v5, v107
	v_exp_f32_e32 v108, v108
	v_exp_f32_e32 v109, v109
	v_exp_f32_e32 v110, v110
	v_exp_f32_e32 v111, v111
	v_cvt_pk_bf16_f32 v140, v104, v105
	v_cvt_pk_bf16_f32 v141, v106, v107
	v_add_f32_e32 v2, v2, v108
	v_add_f32_e32 v3, v3, v109
	v_add_f32_e32 v4, v4, v110
	v_add_f32_e32 v5, v5, v111
	v_add_f32_e32 v2, v2, v3
	v_add_f32_e32 v4, v4, v5
	v_cvt_pk_bf16_f32 v142, v108, v109
	v_add_f32_e32 v2, v2, v4
	v_cvt_pk_bf16_f32 v143, v110, v111
	v_add_f32_e32 v165, v165, v2
	ds_read_b64_tr_b16 v[2:3], v0 offset:32768
	ds_read_b64_tr_b16 v[4:5], v14 offset:32768
	ds_read_b64_tr_b16 v[6:7], v15 offset:32768
	ds_read_b64_tr_b16 v[8:9], v171 offset:32768
	ds_read_b64_tr_b16 v[10:11], v180 offset:32768
	ds_read_b64_tr_b16 v[12:13], v181 offset:32768
	ds_read_b64_tr_b16 v[172:173], v253 offset:32768
	ds_read_b64_tr_b16 v[174:175], v254 offset:32768
	ds_read_b64_tr_b16 v[198:199], v0 offset:36864
	ds_read_b64_tr_b16 v[200:201], v14 offset:36864
	ds_read_b64_tr_b16 v[202:203], v15 offset:36864
	ds_read_b64_tr_b16 v[204:205], v171 offset:36864
	ds_read_b64_tr_b16 v[206:207], v180 offset:36864
	ds_read_b64_tr_b16 v[208:209], v181 offset:36864
	s_setprio 2
	s_waitcnt lgkmcnt(12)
	v_mfma_f32_32x32x16_bf16 v[64:79], v[2:5], v[128:131], v[64:79]
	ds_read_b64_tr_b16 v[176:177], v253 offset:36864
	ds_read_b64_tr_b16 v[178:179], v254 offset:36864
	s_waitcnt lgkmcnt(12)
	v_mfma_f32_32x32x16_bf16 v[48:63], v[6:9], v[128:131], v[48:63]
	ds_read_b64_tr_b16 v[2:3], v0 offset:40960
	ds_read_b64_tr_b16 v[4:5], v14 offset:40960
	s_waitcnt lgkmcnt(12)
	v_mfma_f32_32x32x16_bf16 v[32:47], v[10:13], v[128:131], v[32:47]
	ds_read_b64_tr_b16 v[6:7], v15 offset:40960
	ds_read_b64_tr_b16 v[8:9], v171 offset:40960
	s_waitcnt lgkmcnt(12)
	v_mfma_f32_32x32x16_bf16 v[16:31], v[172:175], v[128:131], v[16:31]
	ds_read_b64_tr_b16 v[10:11], v180 offset:40960
	ds_read_b64_tr_b16 v[12:13], v181 offset:40960
	s_waitcnt lgkmcnt(12)
	v_mfma_f32_32x32x16_bf16 v[64:79], v[198:201], v[132:135], v[64:79]
	ds_read_b64_tr_b16 v[172:173], v253 offset:40960
	ds_read_b64_tr_b16 v[174:175], v254 offset:40960
	s_waitcnt lgkmcnt(12)
	v_mfma_f32_32x32x16_bf16 v[48:63], v[202:205], v[132:135], v[48:63]
	ds_read_b64_tr_b16 v[198:199], v0 offset:45056
	ds_read_b64_tr_b16 v[200:201], v14 offset:45056
	s_waitcnt lgkmcnt(12)
	v_mfma_f32_32x32x16_bf16 v[32:47], v[206:209], v[132:135], v[32:47]
	ds_read_b64_tr_b16 v[202:203], v15 offset:45056
	ds_read_b64_tr_b16 v[204:205], v171 offset:45056
	s_waitcnt lgkmcnt(12)
	v_mfma_f32_32x32x16_bf16 v[16:31], v[176:179], v[132:135], v[16:31]
	ds_read_b64_tr_b16 v[206:207], v180 offset:45056
	ds_read_b64_tr_b16 v[208:209], v181 offset:45056
	s_waitcnt lgkmcnt(12)
	v_mfma_f32_32x32x16_bf16 v[64:79], v[2:5], v[136:139], v[64:79]
	ds_read_b64_tr_b16 v[176:177], v253 offset:45056
	ds_read_b64_tr_b16 v[178:179], v254 offset:45056
	s_waitcnt lgkmcnt(12)
	v_mfma_f32_32x32x16_bf16 v[48:63], v[6:9], v[136:139], v[48:63]
	ds_read_b128 v[2:5], v145
	s_waitcnt lgkmcnt(11)
	v_mfma_f32_32x32x16_bf16 v[32:47], v[10:13], v[136:139], v[32:47]
	ds_read_b128 v[6:9], v145 offset:8192
	s_waitcnt lgkmcnt(10)
	v_mfma_f32_32x32x16_bf16 v[16:31], v[172:175], v[136:139], v[16:31]
	ds_read_b128 v[10:13], v159
	s_waitcnt lgkmcnt(9)
	v_mfma_f32_32x32x16_bf16 v[64:79], v[198:201], v[140:143], v[64:79]
	ds_read_b128 v[172:175], v159 offset:8192
	s_waitcnt lgkmcnt(8)
	v_mfma_f32_32x32x16_bf16 v[48:63], v[202:205], v[140:143], v[48:63]
	ds_read_b128 v[198:201], v160
	s_waitcnt lgkmcnt(7)
	v_mfma_f32_32x32x16_bf16 v[32:47], v[206:209], v[140:143], v[32:47]
	ds_read_b128 v[202:205], v160 offset:8192
	s_waitcnt lgkmcnt(6)
	v_mfma_f32_32x32x16_bf16 v[16:31], v[176:179], v[140:143], v[16:31]
	ds_read_b128 v[206:209], v161
	ds_read_b128 v[176:179], v161 offset:8192
	s_waitcnt lgkmcnt(7)
	v_mfma_f32_32x32x16_bf16 v[80:95], v[2:5], v[112:115], 0
	s_waitcnt lgkmcnt(6)
	v_mfma_f32_32x32x16_bf16 v[96:111], v[6:9], v[112:115], 0
	s_waitcnt lgkmcnt(5)
	v_mfma_f32_32x32x16_bf16 v[80:95], v[10:13], v[116:119], v[80:95]
	s_waitcnt lgkmcnt(4)
	v_mfma_f32_32x32x16_bf16 v[96:111], v[172:175], v[116:119], v[96:111]
	s_waitcnt lgkmcnt(3)
	v_mfma_f32_32x32x16_bf16 v[80:95], v[198:201], v[120:123], v[80:95]
	s_waitcnt lgkmcnt(2)
	v_mfma_f32_32x32x16_bf16 v[96:111], v[202:205], v[120:123], v[96:111]
	s_waitcnt lgkmcnt(1)
	v_mfma_f32_32x32x16_bf16 v[80:95], v[206:209], v[124:127], v[80:95]
	s_waitcnt lgkmcnt(0)
	v_mfma_f32_32x32x16_bf16 v[96:111], v[176:179], v[124:127], v[96:111]
	s_setprio 1
	s_add_u32 s22, s22, 0x20000
	s_addc_u32 s23, s23, 0
	s_add_i32 s95, s95, 1
	s_cmp_lt_i32 s95, s30
	s_waitcnt vmcnt(4)
	s_barrier
	s_cbranch_scc1 .Lc1_st0
	s_mov_b32 s24, 0
	s_mov_b32 s93, 0x4000
	s_mov_b32 s94, 0x8000
	s_branch .LBB0_704

; #define ATT_BAR() do { asm volatile("s_waitcnt lgkmcnt(0)" ::: "memory"); __builtin_amdgcn_s_barrier(); asm volatile("" ::: "memory"); } while (0)
; #define ATT_DMAK(t_, buf_) do { _Pragma("unroll") for (int j = 0; j < 2; ++j) \
;         glds16((const char*)U.K + (size_t)(U.dry ? 0 : (t_)) * (64 * AW * 2) + kdo[j], (unsigned)__builtin_amdgcn_readfirstlane((int)(ldsb + LK + (buf_) + (wid * 2 + j) * 1024))); } while (0)
; #define ATT_DMAV(t_, buf_) do { _Pragma("unroll") for (int j = 0; j < 2; ++j) \
;         glds16((const char*)U.V + (size_t)(U.dry ? 0 : (t_)) * (64 * AW * 2) + vdo[j], (unsigned)__builtin_amdgcn_readfirstlane((int)(ldsb + LV + (buf_) + (wid * 2 + j) * 1024))); } while (0)
; #define ATT_LOADK(t_) do { _Pragma("unroll") for (int i = 0; i < 2; ++i) { \
;         int key = (t_) * 64 + srow + 32 * i; if (key > U.nkeys - 1) key = U.nkeys - 1; \
;         const float* kp = (key < PAST) ? (const float*)U.K + (size_t)key * AW : U.Kn + (size_t)(key - PAST) * AW; \
;         kf4[i][0] = *(const f32x4*)(kp + sch * 8); kf4[i][1] = *(const f32x4*)(kp + sch * 8 + 4); } } while (0)
; #define ATT_WRITEK(buf_) do { _Pragma("unroll") for (int i = 0; i < 2; ++i) *(LAS u32x4*)(lds + LK + (buf_) + kw[i]) = pack8(kf4[i][0], kf4[i][1]); } while (0)
; #define ATT_EVEN(j_, k2_, v1_) do { if (!F32) { if ((j_) + 2 < nt) ATT_DMAK((j_) + 2, k2_); if ((j_) + 1 < nt) ATT_DMAV((j_) + 1, v1_); } } while (0)
; template <bool F32>
; __device__ __forceinline__ void attn_unit(const AUnit& U, LAS unsigned char* lds, float lam, const float* subg) {
;     ...
;     if (!F32) { ATT_DMAK(0, 0); if (nt > 1) ATT_DMAK(1, 16384); ATT_DMAV(0, 0); asm volatile("s_waitcnt vmcnt(0)" ::: "memory"); }
;     else { f32x4 kf4[2][2]; ATT_LOADK(0); ATT_WRITEK(0); }
;     ATT_BAR();
;     int r0 = 32768, r1 = 0, r2 = 16384;
;     if (comp == 0) {
; #pragma unroll 1
;         for (int it = 0; it <= nt; ++it) {
;             ATT_EVEN(it, r0, r2);
;             ATT_MM((it >= 1 && it <= mnt), (it < mnt), r0, r1);
;             if (it < mnt) ATT_SM(it);
;             ATT_ODD(it, r2, r1);
;             ATT_BAR();
;             { const int t_ = r0; r0 = r1; r1 = r2; r2 = t_; }
;         }
.Lc0_st0:
	s_add_u32 s26, s6, 0x1fe0000
	s_addc_u32 s27, s7, 0
	s_mov_b32 m0, s8
	s_nop 0
	global_load_lds_dwordx4 v146, s[6:7]
	s_addk_i32 m0, 0x400
	s_nop 0
	global_load_lds_dwordx4 v148, s[6:7]
	s_add_i32 m0, s28, 0x8000
	s_nop 0
	global_load_lds_dwordx4 v150, s[26:27]
	s_addk_i32 m0, 0x400
	s_nop 0
	global_load_lds_dwordx4 v152, s[26:27]
	ds_read_b64_tr_b16 v[2:3], v0
	ds_read_b64_tr_b16 v[4:5], v14
	ds_read_b64_tr_b16 v[6:7], v15
	ds_read_b64_tr_b16 v[8:9], v171
	ds_read_b64_tr_b16 v[10:11], v180
	ds_read_b64_tr_b16 v[12:13], v181
	ds_read_b64_tr_b16 v[172:173], v253
	ds_read_b64_tr_b16 v[174:175], v254
	ds_read_b64_tr_b16 v[198:199], v0 offset:4096
	ds_read_b64_tr_b16 v[200:201], v14 offset:4096
	ds_read_b64_tr_b16 v[202:203], v15 offset:4096
	ds_read_b64_tr_b16 v[204:205], v171 offset:4096
	ds_read_b64_tr_b16 v[206:207], v180 offset:4096
	ds_read_b64_tr_b16 v[208:209], v181 offset:4096
	s_setprio 2
	s_waitcnt lgkmcnt(12)
	v_mfma_f32_32x32x16_bf16 v[64:79], v[2:5], v[128:131], v[64:79]
	ds_read_b64_tr_b16 v[176:177], v253 offset:4096
	ds_read_b64_tr_b16 v[178:179], v254 offset:4096
	s_waitcnt lgkmcnt(12)
	v_mfma_f32_32x32x16_bf16 v[48:63], v[6:9], v[128:131], v[48:63]
	ds_read_b64_tr_b16 v[2:3], v0 offset:8192
	ds_read_b64_tr_b16 v[4:5], v14 offset:8192
	s_waitcnt lgkmcnt(12)
	v_mfma_f32_32x32x16_bf16 v[32:47], v[10:13], v[128:131], v[32:47]
	ds_read_b64_tr_b16 v[6:7], v15 offset:8192
	ds_read_b64_tr_b16 v[8:9], v171 offset:8192
	s_waitcnt lgkmcnt(12)
	v_mfma_f32_32x32x16_bf16 v[16:31], v[172:175], v[128:131], v[16:31]
	ds_read_b64_tr_b16 v[10:11], v180 offset:8192
	ds_read_b64_tr_b16 v[12:13], v181 offset:8192
	s_waitcnt lgkmcnt(12)
	v_mfma_f32_32x32x16_bf16 v[64:79], v[198:201], v[132:135], v[64:79]
	ds_read_b64_tr_b16 v[172:173], v253 offset:8192
	ds_read_b64_tr_b16 v[174:175], v254 offset:8192
	s_waitcnt lgkmcnt(12)
	v_mfma_f32_32x32x16_bf16 v[48:63], v[202:205], v[132:135], v[48:63]
	ds_read_b64_tr_b16 v[198:199], v0 offset:12288
	ds_read_b64_tr_b16 v[200:201], v14 offset:12288
	s_waitcnt lgkmcnt(12)
	v_mfma_f32_32x32x16_bf16 v[32:47], v[206:209], v[132:135], v[32:47]
	ds_read_b64_tr_b16 v[202:203], v15 offset:12288
	ds_read_b64_tr_b16 v[204:205], v171 offset:12288
	s_waitcnt lgkmcnt(12)
	v_mfma_f32_32x32x16_bf16 v[16:31], v[176:179], v[132:135], v[16:31]
	ds_read_b64_tr_b16 v[206:207], v180 offset:12288
	ds_read_b64_tr_b16 v[208:209], v181 offset:12288
	s_waitcnt lgkmcnt(12)
	v_mfma_f32_32x32x16_bf16 v[64:79], v[2:5], v[136:139], v[64:79]
	ds_read_b64_tr_b16 v[176:177], v253 offset:12288
	ds_read_b64_tr_b16 v[178:179], v254 offset:12288
	s_waitcnt lgkmcnt(12)
	v_mfma_f32_32x32x16_bf16 v[48:63], v[6:9], v[136:139], v[48:63]
	ds_read_b128 v[2:5], v145 offset:16384
	s_waitcnt lgkmcnt(11)
	v_mfma_f32_32x32x16_bf16 v[32:47], v[10:13], v[136:139], v[32:47]
	ds_read_b128 v[6:9], v145 offset:24576
	s_waitcnt lgkmcnt(10)
	v_mfma_f32_32x32x16_bf16 v[16:31], v[172:175], v[136:139], v[16:31]
	ds_read_b128 v[10:13], v159 offset:16384
	s_waitcnt lgkmcnt(9)
	v_mfma_f32_32x32x16_bf16 v[64:79], v[198:201], v[140:143], v[64:79]
	ds_read_b128 v[172:175], v159 offset:24576
	s_waitcnt lgkmcnt(8)
	v_mfma_f32_32x32x16_bf16 v[48:63], v[202:205], v[140:143], v[48:63]
	ds_read_b128 v[198:201], v160 offset:16384
	s_waitcnt lgkmcnt(7)
	v_mfma_f32_32x32x16_bf16 v[32:47], v[206:209], v[140:143], v[32:47]
	ds_read_b128 v[202:205], v160 offset:24576
	s_waitcnt lgkmcnt(6)
	v_mfma_f32_32x32x16_bf16 v[16:31], v[176:179], v[140:143], v[16:31]
	ds_read_b128 v[206:209], v161 offset:16384
	ds_read_b128 v[176:179], v161 offset:24576
	s_waitcnt lgkmcnt(7)
	v_mfma_f32_32x32x16_bf16 v[80:95], v[2:5], v[112:115], 0
	s_waitcnt lgkmcnt(6)
	v_mfma_f32_32x32x16_bf16 v[96:111], v[6:9], v[112:115], 0
	s_waitcnt lgkmcnt(5)
	v_mfma_f32_32x32x16_bf16 v[80:95], v[10:13], v[116:119], v[80:95]
	s_waitcnt lgkmcnt(4)
	v_mfma_f32_32x32x16_bf16 v[96:111], v[172:175], v[116:119], v[96:111]
	s_waitcnt lgkmcnt(3)
	v_mfma_f32_32x32x16_bf16 v[80:95], v[198:201], v[120:123], v[80:95]
	s_waitcnt lgkmcnt(2)
	v_mfma_f32_32x32x16_bf16 v[96:111], v[202:205], v[120:123], v[96:111]
	s_waitcnt lgkmcnt(1)
	v_mfma_f32_32x32x16_bf16 v[80:95], v[206:209], v[124:127], v[80:95]
	s_waitcnt lgkmcnt(0)
	v_mfma_f32_32x32x16_bf16 v[96:111], v[176:179], v[124:127], v[96:111]
	s_setprio 1
	s_add_u32 s6, s6, 0x20000
	s_addc_u32 s7, s7, 0
	s_add_i32 s31, s31, 1
	s_nop 5
	v_exp_f32_e32 v80, v80
	v_exp_f32_e32 v81, v81
	v_exp_f32_e32 v82, v82
	v_exp_f32_e32 v83, v83
	v_exp_f32_e32 v84, v84
	v_exp_f32_e32 v85, v85
	v_exp_f32_e32 v86, v86
	v_exp_f32_e32 v87, v87
	v_add_f32_e32 v2, v80, v84
	v_add_f32_e32 v3, v81, v85
	v_add_f32_e32 v4, v82, v86
	v_add_f32_e32 v5, v83, v87
	v_cvt_pk_bf16_f32 v128, v80, v81
	v_cvt_pk_bf16_f32 v129, v82, v83
	v_exp_f32_e32 v88, v88
	v_exp_f32_e32 v89, v89
	v_exp_f32_e32 v90, v90
	v_exp_f32_e32 v91, v91
	v_cvt_pk_bf16_f32 v130, v84, v85
	v_cvt_pk_bf16_f32 v131, v86, v87
	v_add_f32_e32 v2, v2, v88
	v_add_f32_e32 v3, v3, v89
	v_add_f32_e32 v4, v4, v90
	v_add_f32_e32 v5, v5, v91
	v_exp_f32_e32 v92, v92
	v_exp_f32_e32 v93, v93
	v_exp_f32_e32 v94, v94
	v_exp_f32_e32 v95, v95
	v_cvt_pk_bf16_f32 v132, v88, v89
	v_cvt_pk_bf16_f32 v133, v90, v91
	v_add_f32_e32 v2, v2, v92
	v_add_f32_e32 v3, v3, v93
	v_add_f32_e32 v4, v4, v94
	v_add_f32_e32 v5, v5, v95
	v_exp_f32_e32 v96, v96
	v_exp_f32_e32 v97, v97
	v_exp_f32_e32 v98, v98
	v_exp_f32_e32 v99, v99
	v_cvt_pk_bf16_f32 v134, v92, v93
	v_cvt_pk_bf16_f32 v135, v94, v95
	v_add_f32_e32 v2, v2, v96
	v_add_f32_e32 v3, v3, v97
	v_add_f32_e32 v4, v4, v98
	v_add_f32_e32 v5, v5, v99
	v_exp_f32_e32 v100, v100
	v_exp_f32_e32 v101, v101
	v_exp_f32_e32 v102, v102
	v_exp_f32_e32 v103, v103
	v_cvt_pk_bf16_f32 v136, v96, v97
	v_cvt_pk_bf16_f32 v137, v98, v99
	v_add_f32_e32 v2, v2, v100
	v_add_f32_e32 v3, v3, v101
	v_add_f32_e32 v4, v4, v102
	v_add_f32_e32 v5, v5, v103
	v_exp_f32_e32 v104, v104
	v_exp_f32_e32 v105, v105
	v_exp_f32_e32 v106, v106
	v_exp_f32_e32 v107, v107
	v_cvt_pk_bf16_f32 v138, v100, v101
	v_cvt_pk_bf16_f32 v139, v102, v103
	v_add_f32_e32 v2, v2, v104
	v_add_f32_e32 v3, v3, v105
	v_add_f32_e32 v4, v4, v106
	v_add_f32_e32 v5, v5, v107
	v_exp_f32_e32 v108, v108
	v_exp_f32_e32 v109, v109
	v_exp_f32_e32 v110, v110
	v_exp_f32_e32 v111, v111
	v_cvt_pk_bf16_f32 v140, v104, v105
	v_cvt_pk_bf16_f32 v141, v106, v107
	v_add_f32_e32 v2, v2, v108
	v_add_f32_e32 v3, v3, v109
	v_add_f32_e32 v4, v4, v110
	v_add_f32_e32 v5, v5, v111
	v_add_f32_e32 v2, v2, v3
	v_add_f32_e32 v4, v4, v5
	v_cvt_pk_bf16_f32 v142, v108, v109
	v_add_f32_e32 v2, v2, v4
	v_cvt_pk_bf16_f32 v143, v110, v111
	v_add_f32_e32 v165, v165, v2
	s_cmp_lt_i32 s31, s94
	s_waitcnt vmcnt(4)
	s_barrier
	s_cbranch_scc1 .Lc0_st1
	s_mov_b32 s22, 0x4000
	s_mov_b32 s29, 0x8000
	s_mov_b32 s30, 0
	s_branch .LBB0_735
; #define ATT_BAR() do { asm volatile("s_waitcnt lgkmcnt(0)" ::: "memory"); __builtin_amdgcn_s_barrier(); asm volatile("" ::: "memory"); } while (0)
; #define ATT_DMAK(t_, buf_) do { _Pragma("unroll") for (int j = 0; j < 2; ++j) \
;         glds16((const char*)U.K + (size_t)(U.dry ? 0 : (t_)) * (64 * AW * 2) + kdo[j], (unsigned)__builtin_amdgcn_readfirstlane((int)(ldsb + LK + (buf_) + (wid * 2 + j) * 1024))); } while (0)
; #define ATT_DMAV(t_, buf_) do { _Pragma("unroll") for (int j = 0; j < 2; ++j) \
;         glds16((const char*)U.V + (size_t)(U.dry ? 0 : (t_)) * (64 * AW * 2) + vdo[j], (unsigned)__builtin_amdgcn_readfirstlane((int)(ldsb + LV + (buf_) + (wid * 2 + j) * 1024))); } while (0)
; #define ATT_LOADK(t_) do { _Pragma("unroll") for (int i = 0; i < 2; ++i) { \
;         int key = (t_) * 64 + srow + 32 * i; if (key > U.nkeys - 1) key = U.nkeys - 1; \
;         const float* kp = (key < PAST) ? (const float*)U.K + (size_t)key * AW : U.Kn + (size_t)(key - PAST) * AW; \
;         kf4[i][0] = *(const f32x4*)(kp + sch * 8); kf4[i][1] = *(const f32x4*)(kp + sch * 8 + 4); } } while (0)
; #define ATT_WRITEK(buf_) do { _Pragma("unroll") for (int i = 0; i < 2; ++i) *(LAS u32x4*)(lds + LK + (buf_) + kw[i]) = pack8(kf4[i][0], kf4[i][1]); } while (0)
; #define ATT_EVEN(j_, k2_, v1_) do { if (!F32) { if ((j_) + 2 < nt) ATT_DMAK((j_) + 2, k2_); if ((j_) + 1 < nt) ATT_DMAV((j_) + 1, v1_); } } while (0)
; template <bool F32>
; __device__ __forceinline__ void attn_unit(const AUnit& U, LAS unsigned char* lds, float lam, const float* subg) {
;     ...
;     if (!F32) { ATT_DMAK(0, 0); if (nt > 1) ATT_DMAK(1, 16384); ATT_DMAV(0, 0); asm volatile("s_waitcnt vmcnt(0)" ::: "memory"); }
;     else { f32x4 kf4[2][2]; ATT_LOADK(0); ATT_WRITEK(0); }
;     ATT_BAR();
;     int r0 = 32768, r1 = 0, r2 = 16384;
;     if (comp == 0) {
; #pragma unroll 1
;         for (int it = 0; it <= nt; ++it) {
;             ATT_EVEN(it, r0, r2);
;             ATT_MM((it >= 1 && it <= mnt), (it < mnt), r0, r1);
;             if (it < mnt) ATT_SM(it);
;             ATT_ODD(it, r2, r1);
;             ATT_BAR();
;             { const int t_ = r0; r0 = r1; r1 = r2; r2 = t_; }
;         }
.Lc0_st1:
	s_add_u32 s26, s6, 0x1fe0000
	s_addc_u32 s27, s7, 0
	s_add_i32 m0, s8, 0x4000
	s_nop 0
	global_load_lds_dwordx4 v146, s[6:7]
	s_addk_i32 m0, 0x400
	s_nop 0
	global_load_lds_dwordx4 v148, s[6:7]
	s_mov_b32 m0, s28
	s_nop 0
	global_load_lds_dwordx4 v150, s[26:27]
	s_addk_i32 m0, 0x400
	s_nop 0
	global_load_lds_dwordx4 v152, s[26:27]
	ds_read_b64_tr_b16 v[2:3], v0 offset:16384
	ds_read_b64_tr_b16 v[4:5], v14 offset:16384
	ds_read_b64_tr_b16 v[6:7], v15 offset:16384
	ds_read_b64_tr_b16 v[8:9], v171 offset:16384
	ds_read_b64_tr_b16 v[10:11], v180 offset:16384
	ds_read_b64_tr_b16 v[12:13], v181 offset:16384
	ds_read_b64_tr_b16 v[172:173], v253 offset:16384
	ds_read_b64_tr_b16 v[174:175], v254 offset:16384
	ds_read_b64_tr_b16 v[198:199], v0 offset:20480
	ds_read_b64_tr_b16 v[200:201], v14 offset:20480
	ds_read_b64_tr_b16 v[202:203], v15 offset:20480
	ds_read_b64_tr_b16 v[204:205], v171 offset:20480
	ds_read_b64_tr_b16 v[206:207], v180 offset:20480
	ds_read_b64_tr_b16 v[208:209], v181 offset:20480
	s_setprio 2
	s_waitcnt lgkmcnt(12)
	v_mfma_f32_32x32x16_bf16 v[64:79], v[2:5], v[128:131], v[64:79]
	ds_read_b64_tr_b16 v[176:177], v253 offset:20480
	ds_read_b64_tr_b16 v[178:179], v254 offset:20480
	s_waitcnt lgkmcnt(12)
	v_mfma_f32_32x32x16_bf16 v[48:63], v[6:9], v[128:131], v[48:63]
	ds_read_b64_tr_b16 v[2:3], v0 offset:24576
	ds_read_b64_tr_b16 v[4:5], v14 offset:24576
	s_waitcnt lgkmcnt(12)
	v_mfma_f32_32x32x16_bf16 v[32:47], v[10:13], v[128:131], v[32:47]
	ds_read_b64_tr_b16 v[6:7], v15 offset:24576
	ds_read_b64_tr_b16 v[8:9], v171 offset:24576
	s_waitcnt lgkmcnt(12)
	v_mfma_f32_32x32x16_bf16 v[16:31], v[172:175], v[128:131], v[16:31]
	ds_read_b64_tr_b16 v[10:11], v180 offset:24576
	ds_read_b64_tr_b16 v[12:13], v181 offset:24576
	s_waitcnt lgkmcnt(12)
	v_mfma_f32_32x32x16_bf16 v[64:79], v[198:201], v[132:135], v[64:79]
	ds_read_b64_tr_b16 v[172:173], v253 offset:24576
	ds_read_b64_tr_b16 v[174:175], v254 offset:24576
	s_waitcnt lgkmcnt(12)
	v_mfma_f32_32x32x16_bf16 v[48:63], v[202:205], v[132:135], v[48:63]
	ds_read_b64_tr_b16 v[198:199], v0 offset:28672
	ds_read_b64_tr_b16 v[200:201], v14 offset:28672
	s_waitcnt lgkmcnt(12)
	v_mfma_f32_32x32x16_bf16 v[32:47], v[206:209], v[132:135], v[32:47]
	ds_read_b64_tr_b16 v[202:203], v15 offset:28672
	ds_read_b64_tr_b16 v[204:205], v171 offset:28672
	s_waitcnt lgkmcnt(12)
	v_mfma_f32_32x32x16_bf16 v[16:31], v[176:179], v[132:135], v[16:31]
	ds_read_b64_tr_b16 v[206:207], v180 offset:28672
	ds_read_b64_tr_b16 v[208:209], v181 offset:28672
	s_waitcnt lgkmcnt(12)
	v_mfma_f32_32x32x16_bf16 v[64:79], v[2:5], v[136:139], v[64:79]
	ds_read_b64_tr_b16 v[176:177], v253 offset:28672
	ds_read_b64_tr_b16 v[178:179], v254 offset:28672
	s_waitcnt lgkmcnt(12)
	v_mfma_f32_32x32x16_bf16 v[48:63], v[6:9], v[136:139], v[48:63]
	ds_read_b128 v[2:5], v145 offset:32768
	s_waitcnt lgkmcnt(11)
	v_mfma_f32_32x32x16_bf16 v[32:47], v[10:13], v[136:139], v[32:47]
	ds_read_b128 v[6:9], v145 offset:40960
	s_waitcnt lgkmcnt(10)
	v_mfma_f32_32x32x16_bf16 v[16:31], v[172:175], v[136:139], v[16:31]
	ds_read_b128 v[10:13], v159 offset:32768
	s_waitcnt lgkmcnt(9)
	v_mfma_f32_32x32x16_bf16 v[64:79], v[198:201], v[140:143], v[64:79]
	ds_read_b128 v[172:175], v159 offset:40960
	s_waitcnt lgkmcnt(8)
	v_mfma_f32_32x32x16_bf16 v[48:63], v[202:205], v[140:143], v[48:63]
	ds_read_b128 v[198:201], v160 offset:32768
	s_waitcnt lgkmcnt(7)
	v_mfma_f32_32x32x16_bf16 v[32:47], v[206:209], v[140:143], v[32:47]
	ds_read_b128 v[202:205], v160 offset:40960
	s_waitcnt lgkmcnt(6)
	v_mfma_f32_32x32x16_bf16 v[16:31], v[176:179], v[140:143], v[16:31]
	ds_read_b128 v[206:209], v161 offset:32768
	ds_read_b128 v[176:179], v161 offset:40960
	s_waitcnt lgkmcnt(7)
	v_mfma_f32_32x32x16_bf16 v[80:95], v[2:5], v[112:115], 0
	s_waitcnt lgkmcnt(6)
	v_mfma_f32_32x32x16_bf16 v[96:111], v[6:9], v[112:115], 0
	s_waitcnt lgkmcnt(5)
	v_mfma_f32_32x32x16_bf16 v[80:95], v[10:13], v[116:119], v[80:95]
	s_waitcnt lgkmcnt(4)
	v_mfma_f32_32x32x16_bf16 v[96:111], v[172:175], v[116:119], v[96:111]
	s_waitcnt lgkmcnt(3)
	v_mfma_f32_32x32x16_bf16 v[80:95], v[198:201], v[120:123], v[80:95]
	s_waitcnt lgkmcnt(2)
	v_mfma_f32_32x32x16_bf16 v[96:111], v[202:205], v[120:123], v[96:111]
	s_waitcnt lgkmcnt(1)
	v_mfma_f32_32x32x16_bf16 v[80:95], v[206:209], v[124:127], v[80:95]
	s_waitcnt lgkmcnt(0)
	v_mfma_f32_32x32x16_bf16 v[96:111], v[176:179], v[124:127], v[96:111]
	s_setprio 1
	s_add_u32 s6, s6, 0x20000
	s_addc_u32 s7, s7, 0
	s_add_i32 s31, s31, 1
	s_nop 5
	v_exp_f32_e32 v80, v80
	v_exp_f32_e32 v81, v81
	v_exp_f32_e32 v82, v82
	v_exp_f32_e32 v83, v83
	v_exp_f32_e32 v84, v84
	v_exp_f32_e32 v85, v85
	v_exp_f32_e32 v86, v86
	v_exp_f32_e32 v87, v87
	v_add_f32_e32 v2, v80, v84
	v_add_f32_e32 v3, v81, v85
	v_add_f32_e32 v4, v82, v86
	v_add_f32_e32 v5, v83, v87
	v_cvt_pk_bf16_f32 v128, v80, v81
	v_cvt_pk_bf16_f32 v129, v82, v83
	v_exp_f32_e32 v88, v88
	v_exp_f32_e32 v89, v89
	v_exp_f32_e32 v90, v90
	v_exp_f32_e32 v91, v91
	v_cvt_pk_bf16_f32 v130, v84, v85
	v_cvt_pk_bf16_f32 v131, v86, v87
	v_add_f32_e32 v2, v2, v88
	v_add_f32_e32 v3, v3, v89
	v_add_f32_e32 v4, v4, v90
	v_add_f32_e32 v5, v5, v91
	v_exp_f32_e32 v92, v92
	v_exp_f32_e32 v93, v93
	v_exp_f32_e32 v94, v94
	v_exp_f32_e32 v95, v95
	v_cvt_pk_bf16_f32 v132, v88, v89
	v_cvt_pk_bf16_f32 v133, v90, v91
	v_add_f32_e32 v2, v2, v92
	v_add_f32_e32 v3, v3, v93
	v_add_f32_e32 v4, v4, v94
	v_add_f32_e32 v5, v5, v95
	v_exp_f32_e32 v96, v96
	v_exp_f32_e32 v97, v97
	v_exp_f32_e32 v98, v98
	v_exp_f32_e32 v99, v99
	v_cvt_pk_bf16_f32 v134, v92, v93
	v_cvt_pk_bf16_f32 v135, v94, v95
	v_add_f32_e32 v2, v2, v96
	v_add_f32_e32 v3, v3, v97
	v_add_f32_e32 v4, v4, v98
	v_add_f32_e32 v5, v5, v99
	v_exp_f32_e32 v100, v100
	v_exp_f32_e32 v101, v101
	v_exp_f32_e32 v102, v102
	v_exp_f32_e32 v103, v103
	v_cvt_pk_bf16_f32 v136, v96, v97
	v_cvt_pk_bf16_f32 v137, v98, v99
	v_add_f32_e32 v2, v2, v100
	v_add_f32_e32 v3, v3, v101
	v_add_f32_e32 v4, v4, v102
	v_add_f32_e32 v5, v5, v103
	v_exp_f32_e32 v104, v104
	v_exp_f32_e32 v105, v105
	v_exp_f32_e32 v106, v106
	v_exp_f32_e32 v107, v107
	v_cvt_pk_bf16_f32 v138, v100, v101
	v_cvt_pk_bf16_f32 v139, v102, v103
	v_add_f32_e32 v2, v2, v104
	v_add_f32_e32 v3, v3, v105
	v_add_f32_e32 v4, v4, v106
	v_add_f32_e32 v5, v5, v107
	v_exp_f32_e32 v108, v108
	v_exp_f32_e32 v109, v109
	v_exp_f32_e32 v110, v110
	v_exp_f32_e32 v111, v111
	v_cvt_pk_bf16_f32 v140, v104, v105
	v_cvt_pk_bf16_f32 v141, v106, v107
	v_add_f32_e32 v2, v2, v108
	v_add_f32_e32 v3, v3, v109
	v_add_f32_e32 v4, v4, v110
	v_add_f32_e32 v5, v5, v111
	v_add_f32_e32 v2, v2, v3
	v_add_f32_e32 v4, v4, v5
	v_cvt_pk_bf16_f32 v142, v108, v109
	v_add_f32_e32 v2, v2, v4
	v_cvt_pk_bf16_f32 v143, v110, v111
	v_add_f32_e32 v165, v165, v2
	s_cmp_lt_i32 s31, s94
	s_waitcnt vmcnt(4)
	s_barrier
	s_cbranch_scc1 .Lc0_st2
	s_mov_b32 s22, 0x8000
	s_mov_b32 s29, 0
	s_mov_b32 s30, 0x4000
	s_branch .LBB0_735
; #define ATT_BAR() do { asm volatile("s_waitcnt lgkmcnt(0)" ::: "memory"); __builtin_amdgcn_s_barrier(); asm volatile("" ::: "memory"); } while (0)
; #define ATT_DMAK(t_, buf_) do { _Pragma("unroll") for (int j = 0; j < 2; ++j) \
;         glds16((const char*)U.K + (size_t)(U.dry ? 0 : (t_)) * (64 * AW * 2) + kdo[j], (unsigned)__builtin_amdgcn_readfirstlane((int)(ldsb + LK + (buf_) + (wid * 2 + j) * 1024))); } while (0)
; #define ATT_DMAV(t_, buf_) do { _Pragma("unroll") for (int j = 0; j < 2; ++j) \
;         glds16((const char*)U.V + (size_t)(U.dry ? 0 : (t_)) * (64 * AW * 2) + vdo[j], (unsigned)__builtin_amdgcn_readfirstlane((int)(ldsb + LV + (buf_) + (wid * 2 + j) * 1024))); } while (0)
; #define ATT_LOADK(t_) do { _Pragma("unroll") for (int i = 0; i < 2; ++i) { \
;         int key = (t_) * 64 + srow + 32 * i; if (key > U.nkeys - 1) key = U.nkeys - 1; \
;         const float* kp = (key < PAST) ? (const float*)U.K + (size_t)key * AW : U.Kn + (size_t)(key - PAST) * AW; \
;         kf4[i][0] = *(const f32x4*)(kp + sch * 8); kf4[i][1] = *(const f32x4*)(kp + sch * 8 + 4); } } while (0)
; #define ATT_WRITEK(buf_) do { _Pragma("unroll") for (int i = 0; i < 2; ++i) *(LAS u32x4*)(lds + LK + (buf_) + kw[i]) = pack8(kf4[i][0], kf4[i][1]); } while (0)
; #define ATT_EVEN(j_, k2_, v1_) do { if (!F32) { if ((j_) + 2 < nt) ATT_DMAK((j_) + 2, k2_); if ((j_) + 1 < nt) ATT_DMAV((j_) + 1, v1_); } } while (0)
; template <bool F32>
; __device__ __forceinline__ void attn_unit(const AUnit& U, LAS unsigned char* lds, float lam, const float* subg) {
;     ...
;     if (!F32) { ATT_DMAK(0, 0); if (nt > 1) ATT_DMAK(1, 16384); ATT_DMAV(0, 0); asm volatile("s_waitcnt vmcnt(0)" ::: "memory"); }
;     else { f32x4 kf4[2][2]; ATT_LOADK(0); ATT_WRITEK(0); }
;     ATT_BAR();
;     int r0 = 32768, r1 = 0, r2 = 16384;
;     if (comp == 0) {
; #pragma unroll 1
;         for (int it = 0; it <= nt; ++it) {
;             ATT_EVEN(it, r0, r2);
;             ATT_MM((it >= 1 && it <= mnt), (it < mnt), r0, r1);
;             if (it < mnt) ATT_SM(it);
;             ATT_ODD(it, r2, r1);
;             ATT_BAR();
;             { const int t_ = r0; r0 = r1; r1 = r2; r2 = t_; }
;         }
.Lc0_st2:
	s_add_u32 s26, s6, 0x1fe0000
	s_addc_u32 s27, s7, 0
	s_add_i32 m0, s8, 0x8000
	s_nop 0
	global_load_lds_dwordx4 v146, s[6:7]
	s_addk_i32 m0, 0x400
	s_nop 0
	global_load_lds_dwordx4 v148, s[6:7]
	s_add_i32 m0, s28, 0x4000
	s_nop 0
	global_load_lds_dwordx4 v150, s[26:27]
	s_addk_i32 m0, 0x400
	s_nop 0
	global_load_lds_dwordx4 v152, s[26:27]
	ds_read_b64_tr_b16 v[2:3], v0 offset:32768
	ds_read_b64_tr_b16 v[4:5], v14 offset:32768
	ds_read_b64_tr_b16 v[6:7], v15 offset:32768
	ds_read_b64_tr_b16 v[8:9], v171 offset:32768
	ds_read_b64_tr_b16 v[10:11], v180 offset:32768
	ds_read_b64_tr_b16 v[12:13], v181 offset:32768
	ds_read_b64_tr_b16 v[172:173], v253 offset:32768
	ds_read_b64_tr_b16 v[174:175], v254 offset:32768
	ds_read_b64_tr_b16 v[198:199], v0 offset:36864
	ds_read_b64_tr_b16 v[200:201], v14 offset:36864
	ds_read_b64_tr_b16 v[202:203], v15 offset:36864
	ds_read_b64_tr_b16 v[204:205], v171 offset:36864
	ds_read_b64_tr_b16 v[206:207], v180 offset:36864
	ds_read_b64_tr_b16 v[208:209], v181 offset:36864
	s_setprio 2
	s_waitcnt lgkmcnt(12)
	v_mfma_f32_32x32x16_bf16 v[64:79], v[2:5], v[128:131], v[64:79]
	ds_read_b64_tr_b16 v[176:177], v253 offset:36864
	ds_read_b64_tr_b16 v[178:179], v254 offset:36864
	s_waitcnt lgkmcnt(12)
	v_mfma_f32_32x32x16_bf16 v[48:63], v[6:9], v[128:131], v[48:63]
	ds_read_b64_tr_b16 v[2:3], v0 offset:40960
	ds_read_b64_tr_b16 v[4:5], v14 offset:40960
	s_waitcnt lgkmcnt(12)
	v_mfma_f32_32x32x16_bf16 v[32:47], v[10:13], v[128:131], v[32:47]
	ds_read_b64_tr_b16 v[6:7], v15 offset:40960
	ds_read_b64_tr_b16 v[8:9], v171 offset:40960
	s_waitcnt lgkmcnt(12)
	v_mfma_f32_32x32x16_bf16 v[16:31], v[172:175], v[128:131], v[16:31]
	ds_read_b64_tr_b16 v[10:11], v180 offset:40960
	ds_read_b64_tr_b16 v[12:13], v181 offset:40960
	s_waitcnt lgkmcnt(12)
	v_mfma_f32_32x32x16_bf16 v[64:79], v[198:201], v[132:135], v[64:79]
	ds_read_b64_tr_b16 v[172:173], v253 offset:40960
	ds_read_b64_tr_b16 v[174:175], v254 offset:40960
	s_waitcnt lgkmcnt(12)
	v_mfma_f32_32x32x16_bf16 v[48:63], v[202:205], v[132:135], v[48:63]
	ds_read_b64_tr_b16 v[198:199], v0 offset:45056
	ds_read_b64_tr_b16 v[200:201], v14 offset:45056
	s_waitcnt lgkmcnt(12)
	v_mfma_f32_32x32x16_bf16 v[32:47], v[206:209], v[132:135], v[32:47]
	ds_read_b64_tr_b16 v[202:203], v15 offset:45056
	ds_read_b64_tr_b16 v[204:205], v171 offset:45056
	s_waitcnt lgkmcnt(12)
	v_mfma_f32_32x32x16_bf16 v[16:31], v[176:179], v[132:135], v[16:31]
	ds_read_b64_tr_b16 v[206:207], v180 offset:45056
	ds_read_b64_tr_b16 v[208:209], v181 offset:45056
	s_waitcnt lgkmcnt(12)
	v_mfma_f32_32x32x16_bf16 v[64:79], v[2:5], v[136:139], v[64:79]
	ds_read_b64_tr_b16 v[176:177], v253 offset:45056
	ds_read_b64_tr_b16 v[178:179], v254 offset:45056
	s_waitcnt lgkmcnt(12)
	v_mfma_f32_32x32x16_bf16 v[48:63], v[6:9], v[136:139], v[48:63]
	ds_read_b128 v[2:5], v145
	s_waitcnt lgkmcnt(11)
	v_mfma_f32_32x32x16_bf16 v[32:47], v[10:13], v[136:139], v[32:47]
	ds_read_b128 v[6:9], v145 offset:8192
	s_waitcnt lgkmcnt(10)
	v_mfma_f32_32x32x16_bf16 v[16:31], v[172:175], v[136:139], v[16:31]
	ds_read_b128 v[10:13], v159
	s_waitcnt lgkmcnt(9)
	v_mfma_f32_32x32x16_bf16 v[64:79], v[198:201], v[140:143], v[64:79]
	ds_read_b128 v[172:175], v159 offset:8192
	s_waitcnt lgkmcnt(8)
	v_mfma_f32_32x32x16_bf16 v[48:63], v[202:205], v[140:143], v[48:63]
	ds_read_b128 v[198:201], v160
	s_waitcnt lgkmcnt(7)
	v_mfma_f32_32x32x16_bf16 v[32:47], v[206:209], v[140:143], v[32:47]
	ds_read_b128 v[202:205], v160 offset:8192
	s_waitcnt lgkmcnt(6)
	v_mfma_f32_32x32x16_bf16 v[16:31], v[176:179], v[140:143], v[16:31]
	ds_read_b128 v[206:209], v161
	ds_read_b128 v[176:179], v161 offset:8192
	s_waitcnt lgkmcnt(7)
	v_mfma_f32_32x32x16_bf16 v[80:95], v[2:5], v[112:115], 0
	s_waitcnt lgkmcnt(6)
	v_mfma_f32_32x32x16_bf16 v[96:111], v[6:9], v[112:115], 0
	s_waitcnt lgkmcnt(5)
	v_mfma_f32_32x32x16_bf16 v[80:95], v[10:13], v[116:119], v[80:95]
	s_waitcnt lgkmcnt(4)
	v_mfma_f32_32x32x16_bf16 v[96:111], v[172:175], v[116:119], v[96:111]
	s_waitcnt lgkmcnt(3)
	v_mfma_f32_32x32x16_bf16 v[80:95], v[198:201], v[120:123], v[80:95]
	s_waitcnt lgkmcnt(2)
	v_mfma_f32_32x32x16_bf16 v[96:111], v[202:205], v[120:123], v[96:111]
	s_waitcnt lgkmcnt(1)
	v_mfma_f32_32x32x16_bf16 v[80:95], v[206:209], v[124:127], v[80:95]
	s_waitcnt lgkmcnt(0)
	v_mfma_f32_32x32x16_bf16 v[96:111], v[176:179], v[124:127], v[96:111]
	s_setprio 1
	s_add_u32 s6, s6, 0x20000
	s_addc_u32 s7, s7, 0
	s_add_i32 s31, s31, 1
	s_nop 5
	v_exp_f32_e32 v80, v80
	v_exp_f32_e32 v81, v81
	v_exp_f32_e32 v82, v82
	v_exp_f32_e32 v83, v83
	v_exp_f32_e32 v84, v84
	v_exp_f32_e32 v85, v85
	v_exp_f32_e32 v86, v86
	v_exp_f32_e32 v87, v87
	v_add_f32_e32 v2, v80, v84
	v_add_f32_e32 v3, v81, v85
	v_add_f32_e32 v4, v82, v86
	v_add_f32_e32 v5, v83, v87
	v_cvt_pk_bf16_f32 v128, v80, v81
	v_cvt_pk_bf16_f32 v129, v82, v83
	v_exp_f32_e32 v88, v88
	v_exp_f32_e32 v89, v89
	v_exp_f32_e32 v90, v90
	v_exp_f32_e32 v91, v91
	v_cvt_pk_bf16_f32 v130, v84, v85
	v_cvt_pk_bf16_f32 v131, v86, v87
	v_add_f32_e32 v2, v2, v88
	v_add_f32_e32 v3, v3, v89
	v_add_f32_e32 v4, v4, v90
	v_add_f32_e32 v5, v5, v91
	v_exp_f32_e32 v92, v92
	v_exp_f32_e32 v93, v93
	v_exp_f32_e32 v94, v94
	v_exp_f32_e32 v95, v95
	v_cvt_pk_bf16_f32 v132, v88, v89
	v_cvt_pk_bf16_f32 v133, v90, v91
	v_add_f32_e32 v2, v2, v92
	v_add_f32_e32 v3, v3, v93
	v_add_f32_e32 v4, v4, v94
	v_add_f32_e32 v5, v5, v95
	v_exp_f32_e32 v96, v96
	v_exp_f32_e32 v97, v97
	v_exp_f32_e32 v98, v98
	v_exp_f32_e32 v99, v99
	v_cvt_pk_bf16_f32 v134, v92, v93
	v_cvt_pk_bf16_f32 v135, v94, v95
	v_add_f32_e32 v2, v2, v96
	v_add_f32_e32 v3, v3, v97
	v_add_f32_e32 v4, v4, v98
	v_add_f32_e32 v5, v5, v99
	v_exp_f32_e32 v100, v100
	v_exp_f32_e32 v101, v101
	v_exp_f32_e32 v102, v102
	v_exp_f32_e32 v103, v103
	v_cvt_pk_bf16_f32 v136, v96, v97
	v_cvt_pk_bf16_f32 v137, v98, v99
	v_add_f32_e32 v2, v2, v100
	v_add_f32_e32 v3, v3, v101
	v_add_f32_e32 v4, v4, v102
	v_add_f32_e32 v5, v5, v103
	v_exp_f32_e32 v104, v104
	v_exp_f32_e32 v105, v105
	v_exp_f32_e32 v106, v106
	v_exp_f32_e32 v107, v107
	v_cvt_pk_bf16_f32 v138, v100, v101
	v_cvt_pk_bf16_f32 v139, v102, v103
	v_add_f32_e32 v2, v2, v104
	v_add_f32_e32 v3, v3, v105
	v_add_f32_e32 v4, v4, v106
	v_add_f32_e32 v5, v5, v107
	v_exp_f32_e32 v108, v108
	v_exp_f32_e32 v109, v109
	v_exp_f32_e32 v110, v110
	v_exp_f32_e32 v111, v111
	v_cvt_pk_bf16_f32 v140, v104, v105
	v_cvt_pk_bf16_f32 v141, v106, v107
	v_add_f32_e32 v2, v2, v108
	v_add_f32_e32 v3, v3, v109
	v_add_f32_e32 v4, v4, v110
	v_add_f32_e32 v5, v5, v111
	v_add_f32_e32 v2, v2, v3
	v_add_f32_e32 v4, v4, v5
	v_cvt_pk_bf16_f32 v142, v108, v109
	v_add_f32_e32 v2, v2, v4
	v_cvt_pk_bf16_f32 v143, v110, v111
	v_add_f32_e32 v165, v165, v2
	s_cmp_lt_i32 s31, s94
	s_waitcnt vmcnt(4)
	s_barrier
	s_cbranch_scc1 .Lc0_st0
	s_mov_b32 s22, 0
	s_mov_b32 s29, 0x4000
	s_mov_b32 s30, 0x8000
	s_branch .LBB0_735
